# v5 + MLA loop trims (loop-counter SALU in the MFMA-result wait window, deferred cross-half l sum, half-max test, leaner tile tail) + attention queue order: sample units follow their type
# baseline (speedup 1.0000x reference)
.LBB0_894:
	s_cmpk_lt_i32 s2, 0x180
	s_cbranch_scc1 .Lq_done
	s_cmpk_ge_i32 s2, 0x3c0
	s_cbranch_scc1 .Lq_done
	s_cmpk_lt_i32 s2, 0x1a0
	s_cbranch_scc0 .Lq_1
	s_addk_i32 s2, 0x200
	s_branch .Lq_done
.Lq_1:
	s_cmpk_lt_i32 s2, 0x2a0
	s_cbranch_scc0 .Lq_2
	s_sub_i32 s2, s2, 32
	s_branch .Lq_done
.Lq_2:
	s_cmpk_lt_i32 s2, 0x2c0
	s_cbranch_scc0 .Lq_3
	s_addk_i32 s2, 0x100
	s_branch .Lq_done
.Lq_3:
	s_sub_i32 s2, s2, 64

.LBB0_914:
	s_mov_b32 s0, s97
	s_cmp_ge_i32 s96, s85
	s_cselect_b64 s[94:95], -1, 0
	s_cbranch_scc1 .LBB0_916

.LBB0_916:
	s_sub_i32 s97, s0, 64
	s_cmp_le_i32 s35, s92
	s_cselect_b64 s[2:3], -1, 0
	s_and_b64 s[2:3], s[2:3], s[86:87]
	s_andn2_b64 vcc, exec, s[2:3]
	s_cbranch_vccnz .LBB0_923
	s_mul_i32 s2, s25, 0xa100
	v_add3_u32 v0, s2, v193, v192
	v_add3_u32 v14, s2, v210, v192
	ds_read_b128 v[2:5], v0
	ds_read_b128 v[6:9], v0 offset:12288
	ds_read_b128 v[10:13], v14
	ds_read_b128 v[194:197], v14 offset:12288
	s_cmp_le_i32 s97, s84
	v_add3_u32 v15, s2, v211, v192
	v_add3_u32 v220, s2, v212, v192
	ds_read_b128 v[198:201], v15
	ds_read_b128 v[202:205], v15 offset:12288
	ds_read_b128 v[206:209], v220
	ds_read_b128 v[216:219], v220 offset:12288
	s_waitcnt lgkmcnt(7)
	v_mfma_f32_32x32x16_bf16 v[96:111], v[2:5], v[128:131], v[80:95]
	s_waitcnt lgkmcnt(6)
	v_mfma_f32_32x32x16_bf16 v[112:127], v[6:9], v[128:131], v[80:95]
	s_waitcnt lgkmcnt(5)
	v_mfma_f32_32x32x16_bf16 v[96:111], v[10:13], v[132:135], v[96:111]
	s_waitcnt lgkmcnt(4)
	v_mfma_f32_32x32x16_bf16 v[112:127], v[194:197], v[132:135], v[112:127]
	ds_read_b128 v[2:5], v14 offset:12416
	ds_read_b128 v[6:9], v14 offset:128
	ds_read_b128 v[10:13], v0 offset:12416
	ds_read_b128 v[194:197], v0 offset:128
	s_waitcnt lgkmcnt(7)
	v_mfma_f32_32x32x16_bf16 v[96:111], v[198:201], v[136:139], v[96:111]
	s_waitcnt lgkmcnt(6)
	v_mfma_f32_32x32x16_bf16 v[112:127], v[202:205], v[136:139], v[112:127]
	s_waitcnt lgkmcnt(5)
	v_mfma_f32_32x32x16_bf16 v[96:111], v[206:209], v[140:143], v[96:111]
	s_waitcnt lgkmcnt(4)
	v_mfma_f32_32x32x16_bf16 v[112:127], v[216:219], v[140:143], v[112:127]
	ds_read_b128 v[198:201], v15 offset:128
	ds_read_b128 v[202:205], v15 offset:12416
	ds_read_b128 v[206:209], v220 offset:128
	ds_read_b128 v[216:219], v220 offset:12416
	s_waitcnt lgkmcnt(4)
	v_mfma_f32_32x32x16_bf16 v[96:111], v[194:197], v[144:147], v[96:111]
	v_mfma_f32_32x32x16_bf16 v[112:127], v[10:13], v[144:147], v[112:127]
	v_mfma_f32_32x32x16_bf16 v[96:111], v[6:9], v[148:151], v[96:111]
	v_mfma_f32_32x32x16_bf16 v[112:127], v[2:5], v[148:151], v[112:127]
	ds_read_b128 v[2:5], v14 offset:12544
	ds_read_b128 v[6:9], v14 offset:256
	ds_read_b128 v[10:13], v0 offset:12544
	ds_read_b128 v[194:197], v0 offset:256
	s_waitcnt lgkmcnt(7)
	v_mfma_f32_32x32x16_bf16 v[96:111], v[198:201], v[152:155], v[96:111]
	s_waitcnt lgkmcnt(6)
	v_mfma_f32_32x32x16_bf16 v[112:127], v[202:205], v[152:155], v[112:127]
	s_waitcnt lgkmcnt(5)
	v_mfma_f32_32x32x16_bf16 v[96:111], v[206:209], v[156:159], v[96:111]
	s_waitcnt lgkmcnt(4)
	v_mfma_f32_32x32x16_bf16 v[112:127], v[216:219], v[156:159], v[112:127]
	ds_read_b128 v[198:201], v15 offset:256
	ds_read_b128 v[202:205], v15 offset:12544
	ds_read_b128 v[206:209], v220 offset:256
	ds_read_b128 v[216:219], v220 offset:12544
	s_waitcnt lgkmcnt(4)
	v_mfma_f32_32x32x16_bf16 v[96:111], v[194:197], v[160:163], v[96:111]
	v_mfma_f32_32x32x16_bf16 v[112:127], v[10:13], v[160:163], v[112:127]
	v_mfma_f32_32x32x16_bf16 v[96:111], v[6:9], v[168:171], v[96:111]
	v_mfma_f32_32x32x16_bf16 v[112:127], v[2:5], v[168:171], v[112:127]
	s_waitcnt lgkmcnt(3)
	v_mfma_f32_32x32x16_bf16 v[96:111], v[198:201], v[164:167], v[96:111]
	s_waitcnt lgkmcnt(2)
	v_mfma_f32_32x32x16_bf16 v[112:127], v[202:205], v[164:167], v[112:127]
	s_waitcnt lgkmcnt(1)
	v_mfma_f32_32x32x16_bf16 v[96:111], v[206:209], v[172:175], v[96:111]
	s_waitcnt lgkmcnt(0)
	v_mfma_f32_32x32x16_bf16 v[112:127], v[216:219], v[172:175], v[112:127]
	s_cbranch_scc1 .LBB0_919
	v_add_u32_e32 v0, s0, v191
	v_subrev_u32_e32 v2, 64, v0
	v_cmp_gt_i32_e64 s[52:53], s27, v2
	v_cmp_gt_i32_e32 vcc, s93, v2
	v_subrev_u32_e32 v2, 63, v0
	v_cmp_gt_i32_e64 s[54:55], s27, v2
	v_cmp_gt_i32_e64 s[0:1], s93, v2
	v_subrev_u32_e32 v2, 62, v0
	v_cmp_gt_i32_e64 s[56:57], s27, v2
	v_cmp_gt_i32_e64 s[14:15], s93, v2
	v_subrev_u32_e32 v2, 61, v0
	v_cmp_gt_i32_e64 s[58:59], s27, v2
	v_cmp_gt_i32_e64 s[4:5], s93, v2
	v_subrev_u32_e32 v2, 56, v0
	v_cmp_gt_i32_e64 s[60:61], s27, v2
	v_cmp_gt_i32_e64 s[6:7], s93, v2
	v_subrev_u32_e32 v2, 55, v0
	v_cmp_gt_i32_e64 s[62:63], s27, v2
	v_cmp_gt_i32_e64 s[8:9], s93, v2
	v_subrev_u32_e32 v2, 54, v0
	v_cmp_gt_i32_e64 s[64:65], s27, v2
	v_cmp_gt_i32_e64 s[10:11], s93, v2
	v_subrev_u32_e32 v2, 53, v0
	v_cmp_gt_i32_e64 s[66:67], s27, v2
	v_cmp_gt_i32_e64 s[12:13], s93, v2
	v_subrev_u32_e32 v2, 48, v0
	v_cmp_gt_i32_e64 s[68:69], s27, v2
	v_cmp_gt_i32_e64 s[38:39], s93, v2
	v_subrev_u32_e32 v2, 47, v0
	v_cmp_gt_i32_e64 s[70:71], s27, v2
	v_cmp_gt_i32_e64 s[40:41], s93, v2
	v_subrev_u32_e32 v2, 46, v0
	v_cmp_gt_i32_e64 s[72:73], s27, v2
	v_cmp_gt_i32_e64 s[42:43], s93, v2
	v_subrev_u32_e32 v2, 45, v0
	v_cmp_gt_i32_e64 s[74:75], s27, v2
	v_cmp_gt_i32_e64 s[44:45], s93, v2
	v_subrev_u32_e32 v2, 40, v0
	v_cmp_gt_i32_e64 s[76:77], s27, v2
	v_cmp_gt_i32_e64 s[46:47], s93, v2
	v_subrev_u32_e32 v2, 39, v0
	v_cmp_gt_i32_e64 s[78:79], s27, v2
	v_cmp_gt_i32_e64 s[48:49], s93, v2
	v_subrev_u32_e32 v2, 38, v0
	v_subrev_u32_e32 v0, 37, v0
	v_cmp_gt_i32_e64 s[80:81], s27, v2
	v_cmp_gt_i32_e64 s[82:83], s27, v0
	s_or_b64 s[80:81], s[82:83], s[80:81]
	s_or_b64 s[78:79], s[80:81], s[78:79]
	s_or_b64 s[76:77], s[78:79], s[76:77]
	s_or_b64 s[74:75], s[76:77], s[74:75]
	s_or_b64 s[72:73], s[74:75], s[72:73]
	s_or_b64 s[70:71], s[72:73], s[70:71]
	s_or_b64 s[68:69], s[70:71], s[68:69]
	s_or_b64 s[66:67], s[68:69], s[66:67]
	s_or_b64 s[64:65], s[66:67], s[64:65]
	s_or_b64 s[62:63], s[64:65], s[62:63]
	s_or_b64 s[60:61], s[62:63], s[60:61]
	s_or_b64 s[58:59], s[60:61], s[58:59]
	s_or_b64 s[56:57], s[58:59], s[56:57]
	s_or_b64 s[54:55], s[56:57], s[54:55]
	v_cmp_gt_i32_e64 s[50:51], s93, v2
	v_mov_b32_e32 v2, 0xff800000
	s_or_b64 s[52:53], s[54:55], s[52:53]
	v_cndmask_b32_e64 v96, v2, v96, s[52:53]
	v_cmp_gt_i32_e64 s[52:53], s93, v0
	s_or_b64 s[50:51], s[52:53], s[50:51]
	s_or_b64 s[48:49], s[50:51], s[48:49]
	s_or_b64 s[46:47], s[48:49], s[46:47]
	s_or_b64 s[44:45], s[46:47], s[44:45]
	s_or_b64 s[42:43], s[44:45], s[42:43]
	s_or_b64 s[40:41], s[42:43], s[40:41]
	s_or_b64 s[38:39], s[40:41], s[38:39]
	s_or_b64 s[12:13], s[38:39], s[12:13]
	s_or_b64 s[10:11], s[12:13], s[10:11]
	s_or_b64 s[8:9], s[10:11], s[8:9]
	s_or_b64 s[6:7], s[8:9], s[6:7]
	s_or_b64 s[4:5], s[6:7], s[4:5]
	v_cndmask_b32_e64 v115, v2, v115, s[4:5]
	s_or_b64 s[4:5], s[4:5], s[14:15]
	s_or_b64 s[0:1], s[4:5], s[0:1]
	s_or_b64 vcc, s[0:1], vcc
	v_cndmask_b32_e64 v111, v2, v111, s[82:83]
	v_cndmask_b32_e64 v110, v2, v110, s[80:81]
	v_cndmask_b32_e64 v109, v2, v109, s[78:79]
	v_cndmask_b32_e64 v108, v2, v108, s[76:77]
	v_cndmask_b32_e64 v107, v2, v107, s[74:75]
	v_cndmask_b32_e64 v106, v2, v106, s[72:73]
	v_cndmask_b32_e64 v105, v2, v105, s[70:71]
	v_cndmask_b32_e64 v104, v2, v104, s[68:69]
	v_cndmask_b32_e64 v103, v2, v103, s[66:67]
	v_cndmask_b32_e64 v102, v2, v102, s[64:65]
	v_cndmask_b32_e64 v101, v2, v101, s[62:63]
	v_cndmask_b32_e64 v100, v2, v100, s[60:61]
	v_cndmask_b32_e64 v99, v2, v99, s[58:59]
	v_cndmask_b32_e64 v98, v2, v98, s[56:57]
	v_readlane_b32 s57, v255, 15
	v_readlane_b32 s56, v255, 14
	v_cndmask_b32_e64 v97, v2, v97, s[54:55]
	v_cndmask_b32_e64 v127, v2, v127, s[52:53]
	v_cndmask_b32_e64 v126, v2, v126, s[50:51]
	v_cndmask_b32_e64 v125, v2, v125, s[48:49]
	v_cndmask_b32_e64 v124, v2, v124, s[46:47]
	v_cndmask_b32_e64 v123, v2, v123, s[44:45]
	v_cndmask_b32_e64 v122, v2, v122, s[42:43]
	v_cndmask_b32_e64 v121, v2, v121, s[40:41]
	v_cndmask_b32_e64 v120, v2, v120, s[38:39]
	v_cndmask_b32_e64 v119, v2, v119, s[12:13]
	v_cndmask_b32_e64 v118, v2, v118, s[10:11]
	v_cndmask_b32_e64 v117, v2, v117, s[8:9]
	v_cndmask_b32_e64 v116, v2, v116, s[6:7]
	v_cndmask_b32_e64 v114, v2, v114, s[4:5]
	v_cndmask_b32_e64 v113, v2, v113, s[0:1]
	v_cndmask_b32_e32 v112, v2, v112, vcc
.LBB0_919:
	s_add_i32 s0, s25, 1
	s_cmp_lg_u32 s25, 2
	s_cselect_b32 s25, s0, 0
	s_add_i32 s0, s34, 1
	s_cmp_lg_u32 s34, 2
	s_cselect_b32 s34, s0, 0
	s_add_i32 s96, s96, 1
	s_add_i32 s35, s35, -1
	s_add_u32 s88, s88, 0xfffe0000
	s_addc_u32 s89, s89, -1
	s_add_u32 s20, s20, 0xfffe8000
	s_addc_u32 s21, s21, -1
	v_max3_f32 v0, v96, v97, v98
	v_max3_f32 v2, v112, v113, v114
	v_max3_f32 v0, v0, v99, v100
	v_max3_f32 v2, v2, v115, v116
	v_max3_f32 v0, v0, v101, v102
	v_max3_f32 v2, v2, v117, v118
	v_max3_f32 v0, v0, v103, v104
	v_max3_f32 v2, v2, v119, v120
	v_max3_f32 v0, v0, v105, v106
	v_max3_f32 v2, v2, v121, v122
	v_max3_f32 v0, v0, v107, v108
	v_max3_f32 v2, v2, v123, v124
	v_max3_f32 v0, v0, v109, v110
	v_max3_f32 v2, v2, v125, v126
	v_max3_f32 v0, v0, v111, v127
	v_max_f32_e32 v0, v0, v2
	v_cmp_lt_f32_e32 vcc, 0x41000000, v0
	s_or_b64 s[0:1], s[18:19], vcc
	v_cmp_lg_f32_e32 vcc, 0xff800000, v0
	s_and_b64 s[0:1], s[0:1], vcc
	s_cbranch_scc0 .LBB0_925
	v_mov_b32_e32 v2, v0
	s_nop 1
	v_permlane32_swap_b32_e32 v0, v2
	v_max_f32_e32 v0, v0, v2
	v_cmp_lt_f32_e32 vcc, 0x41000000, v0
	s_or_b64 s[0:1], s[18:19], vcc
	v_cmp_lg_f32_e32 vcc, 0xff800000, v0
	s_and_b64 s[0:1], s[0:1], vcc
	v_cndmask_b32_e64 v0, 0, v0, s[0:1]
	v_exp_f32_e64 v2, -v0
	s_xor_b64 s[0:1], s[0:1], -1
	v_add_f32_e32 v188, v188, v0
	s_or_b64 s[4:5], s[0:1], s[18:19]
	s_and_b64 s[0:1], s[18:19], s[0:1]
	v_xor_b32_e32 v80, 0x80000000, v188
	v_pk_add_f32 v[96:97], v[96:97], v[0:1] op_sel_hi:[1,0] neg_lo:[0,1] neg_hi:[0,1]
	v_pk_add_f32 v[112:113], v[112:113], v[0:1] op_sel_hi:[1,0] neg_lo:[0,1] neg_hi:[0,1]
	v_pk_add_f32 v[98:99], v[98:99], v[0:1] op_sel_hi:[1,0] neg_lo:[0,1] neg_hi:[0,1]
	v_pk_add_f32 v[114:115], v[114:115], v[0:1] op_sel_hi:[1,0] neg_lo:[0,1] neg_hi:[0,1]
	v_pk_add_f32 v[100:101], v[100:101], v[0:1] op_sel_hi:[1,0] neg_lo:[0,1] neg_hi:[0,1]
	v_pk_add_f32 v[116:117], v[116:117], v[0:1] op_sel_hi:[1,0] neg_lo:[0,1] neg_hi:[0,1]
	v_pk_add_f32 v[102:103], v[102:103], v[0:1] op_sel_hi:[1,0] neg_lo:[0,1] neg_hi:[0,1]
	v_pk_add_f32 v[118:119], v[118:119], v[0:1] op_sel_hi:[1,0] neg_lo:[0,1] neg_hi:[0,1]
	v_pk_add_f32 v[104:105], v[104:105], v[0:1] op_sel_hi:[1,0] neg_lo:[0,1] neg_hi:[0,1]
	v_pk_add_f32 v[120:121], v[120:121], v[0:1] op_sel_hi:[1,0] neg_lo:[0,1] neg_hi:[0,1]
	v_pk_add_f32 v[106:107], v[106:107], v[0:1] op_sel_hi:[1,0] neg_lo:[0,1] neg_hi:[0,1]
	v_pk_add_f32 v[122:123], v[122:123], v[0:1] op_sel_hi:[1,0] neg_lo:[0,1] neg_hi:[0,1]
	v_pk_add_f32 v[108:109], v[108:109], v[0:1] op_sel_hi:[1,0] neg_lo:[0,1] neg_hi:[0,1]
	v_pk_add_f32 v[124:125], v[124:125], v[0:1] op_sel_hi:[1,0] neg_lo:[0,1] neg_hi:[0,1]
	v_pk_add_f32 v[110:111], v[110:111], v[0:1] op_sel_hi:[1,0] neg_lo:[0,1] neg_hi:[0,1]
	v_pk_add_f32 v[126:127], v[126:127], v[0:1] op_sel_hi:[1,0] neg_lo:[0,1] neg_hi:[0,1]
	v_cndmask_b32_e64 v0, v2, 1.0, s[4:5]
	s_andn2_b64 s[4:5], s[18:19], exec
	s_and_b64 s[0:1], s[0:1], exec
	s_or_b64 s[18:19], s[4:5], s[0:1]
	v_mov_b32_e32 v81, v80
	v_mov_b32_e32 v82, v80
	v_mov_b32_e32 v83, v80
	v_mov_b32_e32 v84, v80
	v_mov_b32_e32 v85, v80
	v_mov_b32_e32 v86, v80
	v_mov_b32_e32 v87, v80
	v_mov_b32_e32 v88, v80
	v_mov_b32_e32 v89, v80
	v_mov_b32_e32 v90, v80
	v_mov_b32_e32 v91, v80
	v_mov_b32_e32 v92, v80
	v_mov_b32_e32 v93, v80
	v_mov_b32_e32 v94, v80
	v_mov_b32_e32 v95, v80
	s_branch .LBB0_926

.LBB0_926:
	v_exp_f32_e32 v2, v96
	v_exp_f32_e32 v6, v112
	v_exp_f32_e32 v3, v97
	v_exp_f32_e32 v7, v113
	v_exp_f32_e32 v8, v114
	v_add_f32_e32 v10, v6, v2
	v_exp_f32_e32 v4, v98
	v_add_f32_e32 v11, v7, v3
	v_exp_f32_e32 v5, v99
	v_exp_f32_e32 v9, v115
	v_add_f32_e32 v10, v11, v10
	v_add_f32_e32 v11, v8, v4
	v_add_f32_e32 v12, v11, v10
	v_exp_f32_e32 v112, v100
	v_exp_f32_e32 v10, v116
	v_add_f32_e32 v13, v9, v5
	v_exp_f32_e32 v113, v101
	v_exp_f32_e32 v11, v117
	v_add_f32_e32 v12, v13, v12
	v_add_f32_e32 v13, v10, v112
	v_add_f32_e32 v12, v13, v12
	v_exp_f32_e32 v114, v102
	v_exp_f32_e32 v13, v118
	v_add_f32_e32 v14, v11, v113
	v_exp_f32_e32 v115, v103
	v_exp_f32_e32 v15, v119
	v_add_f32_e32 v12, v14, v12
	v_add_f32_e32 v14, v13, v114
	v_add_f32_e32 v96, v14, v12
	v_exp_f32_e32 v102, v104
	v_exp_f32_e32 v12, v120
	v_add_f32_e32 v97, v15, v115
	v_exp_f32_e32 v103, v105
	v_exp_f32_e32 v14, v121
	v_add_f32_e32 v96, v97, v96
	v_add_f32_e32 v97, v12, v102
	v_add_f32_e32 v98, v97, v96
	v_exp_f32_e32 v104, v106
	v_exp_f32_e32 v96, v122
	v_add_f32_e32 v99, v14, v103
	v_exp_f32_e32 v105, v107
	v_exp_f32_e32 v97, v123
	v_add_f32_e32 v98, v99, v98
	v_add_f32_e32 v99, v96, v104
	v_add_f32_e32 v100, v99, v98
	v_exp_f32_e32 v106, v108
	v_exp_f32_e32 v98, v124
	v_add_f32_e32 v101, v97, v105
	v_exp_f32_e32 v107, v109
	v_exp_f32_e32 v99, v125
	v_add_f32_e32 v100, v101, v100
	v_add_f32_e32 v101, v98, v106
	v_add_f32_e32 v116, v101, v100
	v_exp_f32_e32 v108, v110
	v_exp_f32_e32 v100, v126
	v_exp_f32_e32 v109, v111
	v_exp_f32_e32 v101, v127
	v_add_f32_e32 v117, v99, v107
	v_add_f32_e32 v110, v117, v116
	v_add_f32_e32 v111, v100, v108
	v_add_f32_e32 v110, v111, v110
	v_add_f32_e32 v111, v101, v109
	v_add_f32_e32 v110, v111, v110
	v_cmp_gt_f32_e32 vcc, 1.0, v0
	s_cbranch_vccz .LBB0_930
	s_and_saveexec_b64 s[0:1], s[36:37]
	ds_write_b32 v213, v0
	s_or_b64 exec, exec, s[0:1]
	s_waitcnt lgkmcnt(0)
	ds_read_b128 v[116:119], v215 offset:96
	ds_read_b128 v[120:123], v215 offset:64
	ds_read_b128 v[124:127], v215 offset:32
	ds_read_b128 v[194:197], v215
	s_waitcnt lgkmcnt(3)
	v_pk_mul_f32 v[76:77], v[76:77], v[116:117]
	s_waitcnt lgkmcnt(2)
	v_pk_mul_f32 v[72:73], v[72:73], v[120:121]
	s_waitcnt lgkmcnt(1)
	v_pk_mul_f32 v[68:69], v[68:69], v[124:125]
	v_pk_mul_f32 v[78:79], v[78:79], v[118:119]
	v_pk_mul_f32 v[74:75], v[74:75], v[122:123]
	v_pk_mul_f32 v[70:71], v[70:71], v[126:127]
	s_waitcnt lgkmcnt(0)
	v_pk_mul_f32 v[66:67], v[66:67], v[196:197]
	v_pk_mul_f32 v[64:65], v[64:65], v[194:195]
	v_pk_mul_f32 v[60:61], v[60:61], v[116:117]
	v_pk_mul_f32 v[56:57], v[56:57], v[120:121]
	v_pk_mul_f32 v[52:53], v[52:53], v[124:125]
	v_pk_mul_f32 v[62:63], v[62:63], v[118:119]
	v_pk_mul_f32 v[58:59], v[58:59], v[122:123]
	v_pk_mul_f32 v[54:55], v[54:55], v[126:127]
	v_pk_mul_f32 v[50:51], v[50:51], v[196:197]
	v_pk_mul_f32 v[48:49], v[48:49], v[194:195]
	v_pk_mul_f32 v[44:45], v[44:45], v[116:117]
	v_pk_mul_f32 v[40:41], v[40:41], v[120:121]
	v_pk_mul_f32 v[36:37], v[36:37], v[124:125]
	v_pk_mul_f32 v[46:47], v[46:47], v[118:119]
	v_pk_mul_f32 v[42:43], v[42:43], v[122:123]
	v_pk_mul_f32 v[38:39], v[38:39], v[126:127]
	v_pk_mul_f32 v[34:35], v[34:35], v[196:197]
	v_pk_mul_f32 v[32:33], v[32:33], v[194:195]
	v_pk_mul_f32 v[28:29], v[28:29], v[116:117]
	v_pk_mul_f32 v[24:25], v[24:25], v[120:121]
	v_pk_mul_f32 v[20:21], v[20:21], v[124:125]
	v_pk_mul_f32 v[30:31], v[30:31], v[118:119]
	v_pk_mul_f32 v[26:27], v[26:27], v[122:123]
	v_pk_mul_f32 v[22:23], v[22:23], v[126:127]
	v_pk_mul_f32 v[18:19], v[18:19], v[196:197]
	v_pk_mul_f32 v[16:17], v[16:17], v[194:195]
.LBB0_930:
	v_cvt_pk_bf16_f32 v2, v2, v3
	v_cvt_pk_bf16_f32 v3, v4, v5
	v_cvt_pk_bf16_f32 v4, v112, v113
	v_cvt_pk_bf16_f32 v5, v114, v115
	v_cvt_pk_bf16_f32 v102, v102, v103
	v_cvt_pk_bf16_f32 v103, v104, v105
	v_cvt_pk_bf16_f32 v104, v106, v107
	v_cvt_pk_bf16_f32 v105, v108, v109
	v_cvt_pk_bf16_f32 v6, v6, v7
	v_cvt_pk_bf16_f32 v7, v8, v9
	v_cvt_pk_bf16_f32 v8, v10, v11
	v_cvt_pk_bf16_f32 v9, v13, v15
	v_cvt_pk_bf16_f32 v10, v12, v14
	v_cvt_pk_bf16_f32 v11, v96, v97
	v_cvt_pk_bf16_f32 v12, v98, v99
	v_cvt_pk_bf16_f32 v13, v100, v101
	v_fma_f32 v189, v189, v0, v110
	v_add_u32_e32 v0, s2, v214
	ds_read_b64_tr_b16 v[96:97], v0 offset:0x0
	ds_read_b64_tr_b16 v[98:99], v0 offset:0x100
	ds_read_b64_tr_b16 v[106:107], v0 offset:0x1000
	ds_read_b64_tr_b16 v[108:109], v0 offset:0x1100
	ds_read_b64_tr_b16 v[110:111], v0 offset:0x2000
	ds_read_b64_tr_b16 v[112:113], v0 offset:0x2100
	ds_read_b64_tr_b16 v[114:115], v0 offset:0x3000
	ds_read_b64_tr_b16 v[116:117], v0 offset:0x3100
	s_waitcnt lgkmcnt(0)
	s_nop 0
	v_mfma_f32_32x32x16_bf16 v[64:79], v[2:5], v[96:99], v[64:79]
	ds_read_b64_tr_b16 v[96:97], v0 offset:0x200
	ds_read_b64_tr_b16 v[98:99], v0 offset:0x300
	v_mfma_f32_32x32x16_bf16 v[64:79], v[102:105], v[106:109], v[64:79]
	ds_read_b64_tr_b16 v[106:107], v0 offset:0x1200
	ds_read_b64_tr_b16 v[108:109], v0 offset:0x1300
	v_mfma_f32_32x32x16_bf16 v[64:79], v[6:9], v[110:113], v[64:79]
	ds_read_b64_tr_b16 v[110:111], v0 offset:0x2200
	ds_read_b64_tr_b16 v[112:113], v0 offset:0x2300
	v_mfma_f32_32x32x16_bf16 v[64:79], v[10:13], v[114:117], v[64:79]
	ds_read_b64_tr_b16 v[114:115], v0 offset:0x3200
	ds_read_b64_tr_b16 v[116:117], v0 offset:0x3300
	s_waitcnt lgkmcnt(0)
	v_mfma_f32_32x32x16_bf16 v[48:63], v[2:5], v[96:99], v[48:63]
	ds_read_b64_tr_b16 v[96:97], v0 offset:0x400
	ds_read_b64_tr_b16 v[98:99], v0 offset:0x500
	v_mfma_f32_32x32x16_bf16 v[48:63], v[102:105], v[106:109], v[48:63]
	ds_read_b64_tr_b16 v[106:107], v0 offset:0x1400
	ds_read_b64_tr_b16 v[108:109], v0 offset:0x1500
	v_mfma_f32_32x32x16_bf16 v[48:63], v[6:9], v[110:113], v[48:63]
	ds_read_b64_tr_b16 v[110:111], v0 offset:0x2400
	ds_read_b64_tr_b16 v[112:113], v0 offset:0x2500
	v_mfma_f32_32x32x16_bf16 v[48:63], v[10:13], v[114:117], v[48:63]
	ds_read_b64_tr_b16 v[114:115], v0 offset:0x3400
	ds_read_b64_tr_b16 v[116:117], v0 offset:0x3500
	s_waitcnt lgkmcnt(0)
	v_mfma_f32_32x32x16_bf16 v[32:47], v[2:5], v[96:99], v[32:47]
	ds_read_b64_tr_b16 v[96:97], v0 offset:0x600
	ds_read_b64_tr_b16 v[98:99], v0 offset:0x700
	v_mfma_f32_32x32x16_bf16 v[32:47], v[102:105], v[106:109], v[32:47]
	ds_read_b64_tr_b16 v[106:107], v0 offset:0x1600
	ds_read_b64_tr_b16 v[108:109], v0 offset:0x1700
	v_mfma_f32_32x32x16_bf16 v[32:47], v[6:9], v[110:113], v[32:47]
	ds_read_b64_tr_b16 v[110:111], v0 offset:0x2600
	ds_read_b64_tr_b16 v[112:113], v0 offset:0x2700
	v_mfma_f32_32x32x16_bf16 v[32:47], v[10:13], v[114:117], v[32:47]
	ds_read_b64_tr_b16 v[114:115], v0 offset:0x3600
	ds_read_b64_tr_b16 v[116:117], v0 offset:0x3700
	s_waitcnt lgkmcnt(0)
	v_mfma_f32_32x32x16_bf16 v[16:31], v[2:5], v[96:99], v[16:31]
	v_mfma_f32_32x32x16_bf16 v[16:31], v[102:105], v[106:109], v[16:31]
	v_mfma_f32_32x32x16_bf16 v[16:31], v[6:9], v[110:113], v[16:31]
	v_mfma_f32_32x32x16_bf16 v[16:31], v[10:13], v[114:117], v[16:31]
	s_and_b64 vcc, exec, s[94:95]
	s_cbranch_vccnz .Lmla_w0
	s_waitcnt vmcnt(5)
	s_cmp_ge_i32 s96, s26
	s_barrier
	s_cbranch_scc0 .LBB0_914
	s_branch .Lmla_exit
.Lmla_w0:
	s_waitcnt vmcnt(0)
	s_cmp_ge_i32 s96, s26
	s_barrier
	s_cbranch_scc0 .LBB0_914
	s_branch .Lmla_exit

.Lmla_exit:
	v_mov_b32_e32 v225, v189
	s_nop 1
	v_permlane32_swap_b32_e32 v189, v225
	v_add_f32_e32 v189, v189, v225
	s_setprio 0
	v_readlane_b32 s92, v255, 21
	v_readlane_b32 s94, v255, 34
	v_readlane_b32 s84, v255, 35
	v_readlane_b32 s18, v255, 33
	s_branch .LBB0_936
